# gla_c S-state section regenerated by hand: 32 S fragment loads per wave through a 16-quad register ring, first 16 issued a stage early, rest as slots are consumed
# baseline (speedup 1.0000x reference)
.LBB0_828:
	s_or_b64 exec, exec, s[0:1]
	s_waitcnt lgkmcnt(1)
	v_lshl_add_u32 v56, v126, 2, 0
	v_add_u32_e32 v56, 0x10600, v56
	ds_write_b32 v56, v125
	s_waitcnt lgkmcnt(0)
	s_barrier
	ds_read_b32 v56, v88 offset:1024
	s_waitcnt lgkmcnt(0)
	v_cndmask_b32_e64 v57, 0, v56, s[8:9]
	v_cndmask_b32_e64 v58, 0, v56, s[10:11]
	v_cndmask_b32_e64 v57, v58, v57, s[4:5]
	v_add_f32_e32 v2, v2, v57
	v_add_f32_e32 v3, v3, v57
	v_add_f32_e32 v4, v4, v57
	v_add_f32_e32 v5, v5, v57
	v_add_f32_e32 v6, v6, v57
	v_add_f32_e32 v7, v7, v57
	v_add_f32_e32 v8, v8, v57
	v_add_f32_e32 v9, v9, v57
	v_add_f32_e32 v10, v10, v57
	v_add_f32_e32 v11, v11, v57
	v_add_f32_e32 v12, v12, v57
	v_add_f32_e32 v13, v13, v57
	ds_write2_b32 v49, v2, v3 offset0:2 offset1:131
	ds_write2_b32 v51, v4, v5 offset0:4 offset1:133
	ds_write2_b32 v53, v6, v7 offset0:6 offset1:135
	ds_write2_b32 v114, v8, v9 offset0:8 offset1:137
	ds_write2_b32 v117, v10, v11 offset0:10 offset1:139
	ds_write2_b32 v120, v12, v13 offset0:12 offset1:141
	v_add_f32_e32 v2, v0, v57
	v_add_f32_e32 v1, v1, v57
	v_add_f32_e32 v14, v14, v57
	v_add_f32_e32 v15, v15, v57
	v_add_f32_e32 v16, v16, v57
	v_add_f32_e32 v17, v17, v57
	v_add_f32_e32 v18, v18, v57
	v_add_f32_e32 v19, v19, v57
	v_add_f32_e32 v20, v20, v57
	v_add_f32_e32 v21, v21, v57
	v_add_f32_e32 v22, v22, v57
	ds_write2_b32 v112, v2, v1 offset1:129
	ds_write2_b32 v115, v14, v15 offset0:14 offset1:143
	ds_write2_b32 v118, v16, v17 offset0:16 offset1:145
	ds_write2_b32 v121, v18, v19 offset0:18 offset1:147
	ds_write2_b32 v123, v20, v21 offset0:20 offset1:149
	v_add_f32_e32 v1, v23, v57
	ds_write2_b32 v124, v22, v1 offset0:22 offset1:151
	v_add_f32_e32 v1, v24, v57
	v_add_f32_e32 v2, v25, v57
	ds_write2_b32 v122, v1, v2 offset0:24 offset1:153
	v_add_f32_e32 v1, v26, v57
	v_add_f32_e32 v2, v27, v57
	ds_write2_b32 v119, v1, v2 offset0:26 offset1:155
	v_add_f32_e32 v1, v28, v57
	v_add_f32_e32 v2, v29, v57
	ds_write2_b32 v116, v1, v2 offset0:28 offset1:157
	v_add_f32_e32 v1, v54, v57
	v_add_f32_e32 v2, v55, v57
	ds_write2_b32 v113, v1, v2 offset0:30 offset1:159
	s_and_saveexec_b64 s[0:1], s[10:11]
	v_cndmask_b32_e64 v0, v0, v56, s[4:5]
	v_cndmask_b32_e64 v1, v56, v55, s[4:5]
	v_add_f32_e32 v0, v0, v1
	ds_write_b32 v89, v0
	s_or_b64 exec, exec, s[0:1]
	v_or_b32_e32 v2, s44, v144
	v_mov_b64_e32 v[0:1], s[68:69]
	v_mad_i64_i32 v[0:1], s[0:1], v2, s79, v[0:1]
	s_lshl_b32 s70, s70, 1
	v_lshl_add_u64 v[0:1], v[0:1], 0, s[70:71]
	v_mov_b32_e32 v49, v31
	v_lshl_add_u64 v[16:17], v[0:1], 0, v[48:49]
	s_waitcnt vmcnt(0) lgkmcnt(0)
	s_barrier
	v_mov_b32_e32 v12, v150
	v_mov_b32_e32 v13, v151
	v_mov_b32_e32 v14, v152
	v_mov_b32_e32 v15, v153
	v_mov_b32_e32 v8, v154
	v_mov_b32_e32 v9, v155
	v_mov_b32_e32 v10, v156
	v_mov_b32_e32 v11, v157
	v_add_u32_e32 v0, 0x8100, v90
	v_add_u32_e32 v1, 0x8108, v90
	v_add_u32_e32 v2, 0x8110, v90
	ds_read2_b32 v[18:19], v90 offset1:1
	ds_read2_b32 v[20:21], v90 offset0:2 offset1:3
	ds_read2_b32 v[22:23], v90 offset0:4 offset1:5
	ds_read2_b32 v[24:25], v0 offset1:1
	ds_read2_b32 v[26:27], v1 offset1:1
	ds_read2_b32 v[28:29], v2 offset1:1
	v_mov_b32_e32 v4, v158
	v_mov_b32_e32 v5, v159
	v_mov_b32_e32 v6, v160
	v_mov_b32_e32 v7, v161
	v_mov_b32_e32 v0, v162
	v_mov_b32_e32 v1, v163
	v_mov_b32_e32 v2, v164
	v_mov_b32_e32 v3, v165
	s_waitcnt lgkmcnt(5)
	v_mul_f32_e32 v49, 0x3fb8aa3b, v18
	v_mul_f32_e32 v51, 0xbfb8aa3b, v18
	v_mul_f32_e32 v53, 0x3fb8aa3b, v19
	v_mul_f32_e32 v54, 0xbfb8aa3b, v19
	s_waitcnt lgkmcnt(4)
	v_mul_f32_e32 v55, 0x3fb8aa3b, v20
	v_mul_f32_e32 v56, 0xbfb8aa3b, v20
	v_mul_f32_e32 v57, 0x3fb8aa3b, v21
	v_mul_f32_e32 v58, 0xbfb8aa3b, v21
	s_waitcnt lgkmcnt(3)
	v_mul_f32_e32 v59, 0x3fb8aa3b, v22
	v_mul_f32_e32 v60, 0xbfb8aa3b, v22
	v_mul_f32_e32 v61, 0x3fb8aa3b, v23
	v_mul_f32_e32 v62, 0xbfb8aa3b, v23
	s_waitcnt lgkmcnt(2)
	v_mul_f32_e32 v63, 0xbfb8aa3b, v25
	s_waitcnt lgkmcnt(1)
	v_mul_f32_e32 v64, 0x3fb8aa3b, v26
	v_mul_f32_e32 v65, 0xbfb8aa3b, v26
	v_mul_f32_e32 v66, 0x3fb8aa3b, v27
	v_mul_f32_e32 v67, 0xbfb8aa3b, v27
	v_exp_f32_e32 v18, v49
	v_exp_f32_e32 v20, v51
	v_mul_f32_e32 v49, 0x3fb8aa3b, v24
	v_mul_f32_e32 v51, 0xbfb8aa3b, v24
	v_exp_f32_e32 v19, v53
	v_exp_f32_e32 v21, v54
	v_mul_f32_e32 v53, 0x3fb8aa3b, v25
	v_exp_f32_e32 v22, v55
	v_exp_f32_e32 v24, v56
	v_exp_f32_e32 v23, v57
	v_exp_f32_e32 v25, v58
	v_exp_f32_e32 v26, v59
	v_exp_f32_e32 v54, v60
	v_exp_f32_e32 v27, v61
	v_exp_f32_e32 v55, v62
	v_exp_f32_e32 v59, v63
	v_exp_f32_e32 v60, v64
	v_exp_f32_e32 v62, v65
	v_exp_f32_e32 v61, v66
	v_exp_f32_e32 v63, v67
	s_waitcnt lgkmcnt(0)
	v_mul_f32_e32 v68, 0x3fb8aa3b, v28
	v_mul_f32_e32 v70, 0x3fb8aa3b, v29
	v_exp_f32_e32 v64, v68
	v_exp_f32_e32 v65, v70
	v_exp_f32_e32 v56, v49
	v_exp_f32_e32 v57, v53
	v_mul_f32_e32 v28, 0xbfb8aa3b, v28
	v_exp_f32_e32 v28, v28
	v_exp_f32_e32 v58, v51
	s_lshl_b32 s1, s86, 1
	s_lshl_b32 s45, s45, 15
	v_lshlrev_b32_e32 v66, 16, v12
	v_and_b32_e32 v67, 0xffff0000, v12
	v_lshlrev_b32_e32 v12, 16, v13
	v_and_b32_e32 v13, 0xffff0000, v13
	v_lshlrev_b32_e32 v68, 16, v8
	v_and_b32_e32 v69, 0xffff0000, v8
	v_lshlrev_b32_e32 v8, 16, v9
	v_and_b32_e32 v9, 0xffff0000, v9
	v_pk_mul_f32 v[66:67], v[66:67], s[74:75] op_sel_hi:[1,0]
	v_pk_mul_f32 v[12:13], v[12:13], s[74:75] op_sel_hi:[1,0]
	v_pk_mul_f32 v[62:63], v[62:63], v[8:9]
	v_pk_mul_f32 v[24:25], v[24:25], v[8:9]
	v_pk_mul_f32 v[8:9], v[66:67], v[18:19]
	v_pk_mul_f32 v[18:19], v[12:13], v[60:61]
	v_pk_mul_f32 v[12:13], v[12:13], v[22:23]
	v_lshlrev_b32_e32 v22, 16, v14
	v_and_b32_e32 v23, 0xffff0000, v14
	v_mul_f32_e32 v14, 0xbfb8aa3b, v29
	v_pk_mul_f32 v[22:23], v[22:23], s[74:75] op_sel_hi:[1,0]
	v_exp_f32_e32 v29, v14
	v_add_u32_e32 v14, 24, v90
	v_pk_mul_f32 v[60:61], v[22:23], v[64:65]
	v_pk_mul_f32 v[22:23], v[22:23], v[26:27]
	ds_read2st64_b32 v[26:27], v14 offset1:129
	v_pk_mul_f32 v[56:57], v[66:67], v[56:57]
	ds_read2st64_b32 v[66:67], v91 offset1:129
	v_lshlrev_b32_e32 v64, 16, v10
	v_and_b32_e32 v65, 0xffff0000, v10
	s_waitcnt lgkmcnt(1)
	v_mul_f32_e32 v10, 0x3fb8aa3b, v26
	v_pk_mul_f32 v[28:29], v[28:29], v[64:65]
	v_pk_mul_f32 v[54:55], v[54:55], v[64:65]
	v_exp_f32_e32 v64, v10
	v_mul_f32_e32 v10, 0xbfb8aa3b, v26
	v_exp_f32_e32 v26, v10
	v_mul_f32_e32 v10, 0x3fb8aa3b, v27
	v_pk_mul_f32 v[58:59], v[58:59], v[68:69]
	v_pk_mul_f32 v[20:21], v[20:21], v[68:69]
	v_exp_f32_e32 v68, v10
	v_mul_f32_e32 v10, 0xbfb8aa3b, v27
	v_exp_f32_e32 v14, v10
	s_waitcnt lgkmcnt(0)
	v_mul_f32_e32 v10, 0x3fb8aa3b, v66
	v_exp_f32_e32 v65, v10
	v_mul_f32_e32 v10, 0xbfb8aa3b, v66
	v_exp_f32_e32 v27, v10
	v_mul_f32_e32 v10, 0x3fb8aa3b, v67
	v_exp_f32_e32 v69, v10
	v_mul_f32_e32 v10, 0xbfb8aa3b, v67
	v_lshlrev_b32_e32 v70, 16, v15
	v_and_b32_e32 v71, 0xffff0000, v15
	v_exp_f32_e32 v15, v10
	v_pk_mul_f32 v[70:71], v[70:71], s[74:75] op_sel_hi:[1,0]
	v_lshlrev_b32_e32 v10, 16, v11
	v_pk_mul_f32 v[64:65], v[70:71], v[64:65]
	v_and_b32_e32 v11, 0xffff0000, v11
	v_pk_mul_f32 v[14:15], v[14:15], v[10:11]
	v_pk_mul_f32 v[26:27], v[26:27], v[10:11]
	v_cvt_pk_bf16_f32 v8, v8, v9
	v_cvt_pk_bf16_f32 v9, v12, v13
	v_cvt_pk_bf16_f32 v10, v22, v23
	v_cvt_pk_bf16_f32 v11, v64, v65
	v_pk_mul_f32 v[68:69], v[70:71], v[68:69]
	ds_write_b128 v92, v[8:11]
	v_cvt_pk_bf16_f32 v8, v20, v21
	v_cvt_pk_bf16_f32 v9, v24, v25
	v_cvt_pk_bf16_f32 v10, v54, v55
	v_cvt_pk_bf16_f32 v11, v26, v27
	ds_write_b128 v92, v[8:11] offset:17408
	v_cvt_pk_bf16_f32 v8, v56, v57
	v_cvt_pk_bf16_f32 v9, v18, v19
	v_cvt_pk_bf16_f32 v10, v60, v61
	v_cvt_pk_bf16_f32 v11, v68, v69
	ds_write_b128 v92, v[8:11] offset:34816
	v_cvt_pk_bf16_f32 v8, v58, v59
	v_cvt_pk_bf16_f32 v9, v62, v63
	v_cvt_pk_bf16_f32 v10, v28, v29
	v_cvt_pk_bf16_f32 v11, v14, v15
	ds_write_b128 v92, v[8:11] offset:52224
	ds_read2_b32 v[8:9], v90 offset0:64 offset1:65
	v_add_u32_e32 v10, 0x8200, v90
	ds_read2_b32 v[10:11], v10 offset1:1
	ds_read2_b32 v[12:13], v90 offset0:66 offset1:67
	ds_read2_b32 v[14:15], v90 offset0:68 offset1:69
	ds_read2_b32 v[18:19], v90 offset0:70 offset1:71
	v_add_u32_e32 v21, 0x8208, v90
	v_add_u32_e32 v24, 0x8210, v90
	v_add_u32_e32 v26, 0x8218, v90
	ds_read2_b32 v[22:23], v21 offset1:1
	ds_read2_b32 v[24:25], v24 offset1:1
	ds_read2_b32 v[26:27], v26 offset1:1
	s_waitcnt lgkmcnt(6)
	v_mul_f32_e32 v21, 0x3fb8aa3b, v10
	v_mul_f32_e32 v20, 0x3fb8aa3b, v8
	v_exp_f32_e32 v28, v21
	v_mul_f32_e32 v21, 0x3fb8aa3b, v9
	v_mul_f32_e32 v29, 0x3fb8aa3b, v11
	v_exp_f32_e32 v20, v20
	v_mul_f32_e32 v8, 0xbfb8aa3b, v8
	v_mul_f32_e32 v10, 0xbfb8aa3b, v10
	v_exp_f32_e32 v21, v21
	v_mul_f32_e32 v9, 0xbfb8aa3b, v9
	v_exp_f32_e32 v29, v29
	v_lshlrev_b32_e32 v54, 16, v4
	v_and_b32_e32 v55, 0xffff0000, v4
	v_mul_f32_e32 v4, 0xbfb8aa3b, v11
	v_exp_f32_e32 v8, v8
	v_exp_f32_e32 v10, v10
	v_exp_f32_e32 v9, v9
	v_exp_f32_e32 v11, v4
	v_pk_mul_f32 v[54:55], v[54:55], s[74:75] op_sel_hi:[1,0]
	v_lshlrev_b32_e32 v58, 16, v5
	v_pk_mul_f32 v[28:29], v[54:55], v[28:29]
	v_pk_mul_f32 v[20:21], v[54:55], v[20:21]
	v_lshlrev_b32_e32 v54, 16, v0
	v_and_b32_e32 v55, 0xffff0000, v0
	s_waitcnt lgkmcnt(5)
	v_mul_f32_e32 v0, 0x3fb8aa3b, v12
	v_pk_mul_f32 v[10:11], v[10:11], v[54:55]
	v_pk_mul_f32 v[8:9], v[8:9], v[54:55]
	v_exp_f32_e32 v54, v0
	v_mul_f32_e32 v0, 0xbfb8aa3b, v12
	v_exp_f32_e32 v12, v0
	s_waitcnt lgkmcnt(2)
	v_mul_f32_e32 v0, 0x3fb8aa3b, v22
	v_exp_f32_e32 v56, v0
	v_mul_f32_e32 v0, 0xbfb8aa3b, v22
	v_exp_f32_e32 v4, v0
	v_mul_f32_e32 v0, 0x3fb8aa3b, v13
	v_exp_f32_e32 v55, v0
	v_mul_f32_e32 v0, 0xbfb8aa3b, v13
	v_exp_f32_e32 v13, v0
	v_mul_f32_e32 v0, 0x3fb8aa3b, v23
	v_exp_f32_e32 v57, v0
	v_mul_f32_e32 v0, 0xbfb8aa3b, v23
	v_and_b32_e32 v59, 0xffff0000, v5
	v_exp_f32_e32 v5, v0
	v_lshlrev_b32_e32 v0, 16, v1
	v_and_b32_e32 v1, 0xffff0000, v1
	v_pk_mul_f32 v[12:13], v[12:13], v[0:1]
	v_pk_mul_f32 v[4:5], v[4:5], v[0:1]
	v_mul_f32_e32 v1, 0xbfb8aa3b, v14
	v_pk_mul_f32 v[58:59], v[58:59], s[74:75] op_sel_hi:[1,0]
	v_mul_f32_e32 v0, 0x3fb8aa3b, v14
	v_exp_f32_e32 v14, v1
	s_waitcnt lgkmcnt(1)
	v_mul_f32_e32 v1, 0x3fb8aa3b, v24
	v_pk_mul_f32 v[22:23], v[58:59], v[54:55]
	v_exp_f32_e32 v54, v1
	v_mul_f32_e32 v1, 0xbfb8aa3b, v24
	v_exp_f32_e32 v24, v1
	v_mul_f32_e32 v1, 0x3fb8aa3b, v15
	v_mul_f32_e32 v49, 0x3fb8aa3b, v25
	v_pk_mul_f32 v[56:57], v[58:59], v[56:57]
	v_exp_f32_e32 v0, v0
	v_exp_f32_e32 v1, v1
	v_mul_f32_e32 v15, 0xbfb8aa3b, v15
	v_exp_f32_e32 v55, v49
	v_lshlrev_b32_e32 v58, 16, v6
	v_and_b32_e32 v59, 0xffff0000, v6
	v_mul_f32_e32 v6, 0xbfb8aa3b, v25
	v_exp_f32_e32 v15, v15
	v_exp_f32_e32 v25, v6
	v_pk_mul_f32 v[58:59], v[58:59], s[74:75] op_sel_hi:[1,0]
	v_lshlrev_b32_e32 v62, 16, v7
	v_pk_mul_f32 v[54:55], v[58:59], v[54:55]
	v_pk_mul_f32 v[58:59], v[58:59], v[0:1]
	v_lshlrev_b32_e32 v0, 16, v2
	v_and_b32_e32 v1, 0xffff0000, v2
	v_pk_mul_f32 v[24:25], v[24:25], v[0:1]
	v_pk_mul_f32 v[14:15], v[14:15], v[0:1]
	v_mul_f32_e32 v1, 0xbfb8aa3b, v18
	v_mul_f32_e32 v0, 0x3fb8aa3b, v18
	v_exp_f32_e32 v18, v1
	s_waitcnt lgkmcnt(0)
	v_mul_f32_e32 v1, 0x3fb8aa3b, v26
	v_exp_f32_e32 v60, v1
	v_mul_f32_e32 v1, 0xbfb8aa3b, v26
	v_mul_f32_e32 v2, 0xbfb8aa3b, v19
	v_exp_f32_e32 v6, v1
	v_mul_f32_e32 v1, 0x3fb8aa3b, v19
	v_exp_f32_e32 v19, v2
	v_mul_f32_e32 v2, 0x3fb8aa3b, v27
	v_exp_f32_e32 v0, v0
	v_exp_f32_e32 v1, v1
	v_exp_f32_e32 v61, v2
	v_mul_f32_e32 v2, 0xbfb8aa3b, v27
	v_and_b32_e32 v63, 0xffff0000, v7
	v_exp_f32_e32 v7, v2
	v_pk_mul_f32 v[62:63], v[62:63], s[74:75] op_sel_hi:[1,0]
	v_cvt_pk_bf16_f32 v2, v58, v59
	v_pk_mul_f32 v[26:27], v[62:63], v[0:1]
	v_lshlrev_b32_e32 v0, 16, v3
	v_and_b32_e32 v1, 0xffff0000, v3
	v_pk_mul_f32 v[6:7], v[6:7], v[0:1]
	v_pk_mul_f32 v[18:19], v[18:19], v[0:1]
	v_cvt_pk_bf16_f32 v0, v20, v21
	v_cvt_pk_bf16_f32 v1, v22, v23
	v_cvt_pk_bf16_f32 v3, v26, v27
	v_pk_mul_f32 v[60:61], v[62:63], v[60:61]
	ds_write_b128 v92, v[0:3] offset:128
	v_cvt_pk_bf16_f32 v0, v8, v9
	v_cvt_pk_bf16_f32 v1, v12, v13
	v_cvt_pk_bf16_f32 v2, v14, v15
	v_cvt_pk_bf16_f32 v3, v18, v19
	ds_write_b128 v92, v[0:3] offset:17536
	v_cvt_pk_bf16_f32 v0, v28, v29
	v_cvt_pk_bf16_f32 v1, v56, v57
	v_cvt_pk_bf16_f32 v2, v54, v55
	v_cvt_pk_bf16_f32 v3, v60, v61
	ds_write_b128 v92, v[0:3] offset:34944
	v_cvt_pk_bf16_f32 v0, v10, v11
	v_cvt_pk_bf16_f32 v1, v4, v5
	v_cvt_pk_bf16_f32 v2, v24, v25
	v_cvt_pk_bf16_f32 v3, v6, v7
	ds_write_b128 v92, v[0:3] offset:52352
	s_waitcnt lgkmcnt(0)
	s_barrier
	v_mov_b32_e32 v0, v166
	v_mov_b32_e32 v1, v167
	v_mov_b32_e32 v2, v168
	v_mov_b32_e32 v3, v169
	v_mov_b32_e32 v4, v170
	v_mov_b32_e32 v5, v171
	v_mov_b32_e32 v6, v172
	v_mov_b32_e32 v7, v173
	s_lshl_b32 s98, s85, 3
	s_lshl_b32 s99, s86, 1
	s_or_b32 s98, s99, s98
	s_ashr_i32 s99, s98, 31
	s_or_b32 s100, s98, 1
	s_ashr_i32 s101, s100, 31
	s_lshl_b64 s[98:99], s[98:99], 21
	s_lshl_b64 s[100:101], s[100:101], 21
	s_add_u32 s98, s98, s52
	s_addc_u32 s99, s99, s53
	s_add_u32 s100, s100, s52
	s_addc_u32 s101, s101, s53
	s_add_u32 s98, s98, s45
	s_addc_u32 s99, s99, 0
	s_add_u32 s100, s100, s45
	s_addc_u32 s101, s101, 0
	v_lshl_add_u64 v[210:211], v[36:37], 0, s[98:99]
	v_lshl_add_u64 v[210:211], v[210:211], 0, v[30:31]
	global_load_dwordx4 v[150:153], v[210:211], off
	global_load_dwordx4 v[154:157], v[210:211], off offset:64
	global_load_dwordx4 v[158:161], v[210:211], off offset:128
	global_load_dwordx4 v[162:165], v[210:211], off offset:192
	v_lshl_add_u64 v[210:211], v[36:37], 0, s[100:101]
	v_lshl_add_u64 v[210:211], v[210:211], 0, v[30:31]
	global_load_dwordx4 v[166:169], v[210:211], off
	global_load_dwordx4 v[170:173], v[210:211], off offset:64
	global_load_dwordx4 v[186:189], v[210:211], off offset:128
	global_load_dwordx4 v[190:193], v[210:211], off offset:192
	v_lshl_add_u64 v[210:211], v[38:39], 0, s[98:99]
	v_lshl_add_u64 v[210:211], v[210:211], 0, v[30:31]
	global_load_dwordx4 v[194:197], v[210:211], off
	global_load_dwordx4 v[198:201], v[210:211], off offset:64
	global_load_dwordx4 v[202:205], v[210:211], off offset:128
	global_load_dwordx4 v[206:209], v[210:211], off offset:192
	v_lshl_add_u64 v[210:211], v[38:39], 0, s[100:101]
	v_lshl_add_u64 v[210:211], v[210:211], 0, v[30:31]
	global_load_dwordx4 v[228:231], v[210:211], off
	global_load_dwordx4 v[232:235], v[210:211], off offset:64
	global_load_dwordx4 v[236:239], v[210:211], off offset:128
	global_load_dwordx4 v[240:243], v[210:211], off offset:192
	ds_write_b16 v103, v0
	ds_write_b16_d16_hi v103, v0 offset:144
	ds_write_b16 v103, v1 offset:288
	ds_write_b16_d16_hi v103, v1 offset:432
	ds_write_b16 v103, v2 offset:576
	ds_write_b16_d16_hi v103, v2 offset:720
	ds_write_b16 v103, v3 offset:864
	ds_write_b16_d16_hi v104, v3
	ds_write_b16 v103, v4 offset:9216
	ds_write_b16_d16_hi v103, v4 offset:9360
	ds_write_b16 v103, v5 offset:9504
	ds_write_b16_d16_hi v103, v5 offset:9648
	ds_write_b16 v103, v6 offset:9792
	ds_write_b16_d16_hi v103, v6 offset:9936
	ds_write_b16 v103, v7 offset:10080
	ds_write_b16_d16_hi v103, v7 offset:10224
	ds_read_b128 v[0:3], v93
	ds_read_b128 v[4:7], v95 offset:17408
	ds_read_b128 v[8:11], v94
	ds_read_b128 v[12:15], v93 offset:64
	ds_read_b128 v[16:19], v95 offset:17472
	s_waitcnt lgkmcnt(3)
	v_mfma_f32_16x16x32_bf16 v[0:3], v[0:3], v[4:7], 0
	ds_read_b128 v[4:7], v95 offset:52224
	ds_read_b128 v[20:23], v94 offset:64
	ds_read_b128 v[24:27], v95 offset:52288
	s_waitcnt lgkmcnt(2)
	v_mfma_f32_16x16x32_bf16 v[4:7], v[8:11], v[4:7], 0
	v_mfma_f32_16x16x32_bf16 v[0:3], v[12:15], v[16:19], v[0:3]
	ds_read_b128 v[8:11], v93 offset:128
	ds_read_b128 v[12:15], v95 offset:17536
	s_waitcnt lgkmcnt(2)
	v_mfma_f32_16x16x32_bf16 v[4:7], v[20:23], v[24:27], v[4:7]
	ds_read_b128 v[16:19], v94 offset:128
	ds_read_b128 v[20:23], v93 offset:192
	ds_read_b128 v[24:27], v95 offset:17600
	s_waitcnt lgkmcnt(3)
	v_mfma_f32_16x16x32_bf16 v[0:3], v[8:11], v[12:15], v[0:3]
	ds_read_b128 v[8:11], v95 offset:52352
	ds_read_b128 v[12:15], v94 offset:192
	ds_read_b128 v[54:57], v95 offset:52416
	s_waitcnt lgkmcnt(2)
	v_mfma_f32_16x16x32_bf16 v[4:7], v[16:19], v[8:11], v[4:7]
	v_mfma_f32_16x16x32_bf16 v[0:3], v[20:23], v[24:27], v[0:3]
	s_waitcnt lgkmcnt(0)
	v_mfma_f32_16x16x32_bf16 v[4:7], v[12:15], v[54:57], v[4:7]
	s_nop 5
	v_cndmask_b32_e64 v0, v0, 0, s[12:13]
	s_nop 0
	v_cndmask_b32_e64 v4, v4, 0, s[14:15]
	v_add_f32_e32 v0, v0, v4
	v_cvt_pk_bf16_f32 v0, v0, s0
	ds_write_b16 v105, v0 offset:18432
	v_cndmask_b32_e64 v0, v1, 0, s[16:17]
	v_cndmask_b32_e64 v1, 0, v5, s[12:13]
	v_add_f32_e32 v0, v0, v1
	v_cvt_pk_bf16_f32 v0, v0, s0
	ds_write_b16 v105, v0 offset:18576
	v_cndmask_b32_e64 v0, v2, 0, s[18:19]
	v_cndmask_b32_e64 v1, v6, 0, s[20:21]
	v_add_f32_e32 v0, v0, v1
	v_cvt_pk_bf16_f32 v0, v0, s0
	ds_write_b16 v105, v0 offset:18720
	v_cndmask_b32_e64 v0, v3, 0, s[22:23]
	v_cndmask_b32_e64 v1, v7, 0, s[24:25]
	v_add_f32_e32 v0, v0, v1
	v_cvt_pk_bf16_f32 v0, v0, s0
	ds_write_b16 v105, v0 offset:18864
	ds_read_b128 v[0:3], v93
	ds_read_b128 v[4:7], v96 offset:17408
	ds_read_b128 v[8:11], v94
	ds_read_b128 v[12:15], v93 offset:64
	ds_read_b128 v[16:19], v96 offset:17472
	s_waitcnt lgkmcnt(3)
	v_mfma_f32_16x16x32_bf16 v[0:3], v[0:3], v[4:7], 0
	ds_read_b128 v[4:7], v96 offset:52224
	ds_read_b128 v[20:23], v94 offset:64
	ds_read_b128 v[24:27], v96 offset:52288
	s_waitcnt lgkmcnt(2)
	v_mfma_f32_16x16x32_bf16 v[4:7], v[8:11], v[4:7], 0
	v_mfma_f32_16x16x32_bf16 v[0:3], v[12:15], v[16:19], v[0:3]
	ds_read_b128 v[8:11], v93 offset:128
	ds_read_b128 v[12:15], v96 offset:17536
	s_waitcnt lgkmcnt(2)
	v_mfma_f32_16x16x32_bf16 v[4:7], v[20:23], v[24:27], v[4:7]
	ds_read_b128 v[16:19], v94 offset:128
	ds_read_b128 v[20:23], v93 offset:192
	ds_read_b128 v[24:27], v96 offset:17600
	s_waitcnt lgkmcnt(3)
	v_mfma_f32_16x16x32_bf16 v[0:3], v[8:11], v[12:15], v[0:3]
	ds_read_b128 v[8:11], v96 offset:52352
	ds_read_b128 v[12:15], v94 offset:192
	ds_read_b128 v[54:57], v96 offset:52416
	s_waitcnt lgkmcnt(2)
	v_mfma_f32_16x16x32_bf16 v[4:7], v[16:19], v[8:11], v[4:7]
	v_mfma_f32_16x16x32_bf16 v[0:3], v[20:23], v[24:27], v[0:3]
	s_waitcnt lgkmcnt(0)
	v_mfma_f32_16x16x32_bf16 v[4:7], v[12:15], v[54:57], v[4:7]
	s_nop 5
	v_cndmask_b32_e64 v0, v0, 0, s[26:27]
	s_nop 0
	v_cndmask_b32_e64 v4, v4, 0, s[28:29]
	v_add_f32_e32 v0, v0, v4
	v_cvt_pk_bf16_f32 v0, v0, s0
	ds_write_b16 v105, v0 offset:18464
	v_cndmask_b32_e64 v0, v1, 0, s[30:31]
	v_cndmask_b32_e64 v1, 0, v5, s[26:27]
	v_add_f32_e32 v0, v0, v1
	v_cvt_pk_bf16_f32 v0, v0, s0
	ds_write_b16 v105, v0 offset:18608
	v_cndmask_b32_e64 v0, v2, 0, s[34:35]
	v_cndmask_b32_e64 v1, v6, 0, s[36:37]
	v_add_f32_e32 v0, v0, v1
	v_cvt_pk_bf16_f32 v0, v0, s0
	ds_write_b16 v105, v0 offset:18752
	v_cndmask_b32_e64 v0, v3, 0, s[38:39]
	v_cndmask_b32_e64 v1, v7, 0, s[40:41]
	v_add_f32_e32 v0, v0, v1
	v_cvt_pk_bf16_f32 v0, v0, s0
	s_lshl_b32 s0, s85, 3
	s_or_b32 s0, s1, s0
	s_ashr_i32 s1, s0, 31
	s_lshl_b64 s[46:47], s[0:1], 21
	s_or_b32 s0, s0, 1
	s_ashr_i32 s1, s0, 31
	s_lshl_b64 s[0:1], s[0:1], 21
	s_add_u32 s48, s52, s0
	s_addc_u32 s49, s53, s1
	s_add_u32 s0, s52, s46
	s_addc_u32 s1, s53, s47
	s_add_u32 s0, s0, s45
	s_addc_u32 s1, s1, 0
	v_lshl_add_u64 v[28:29], s[0:1], 0, v[30:31]
	v_lshl_add_u64 v[24:25], v[28:29], 0, v[36:37]
	ds_write_b16 v105, v0 offset:18896
	s_waitcnt lgkmcnt(0)
	s_barrier
	ds_read_b128 v[16:19], v106 offset:18432
	ds_read_b128 v[20:23], v106 offset:18496
	ds_read_b128 v[58:61], v107
	ds_read_b128 v[74:77], v107 offset:64
	ds_read_b128 v[54:57], v98
	ds_read_b128 v[62:65], v98 offset:64
	ds_read_b128 v[66:69], v98 offset:128
	ds_read_b128 v[70:73], v98 offset:192
	ds_read_b128 v[24:27], v98 offset:34816
	ds_read_b128 v[78:81], v98 offset:34880
	ds_read_b128 v[114:117], v98 offset:34944
	ds_read_b128 v[118:121], v98 offset:35008
	ds_read_b128 v[122:125], v107 offset:2304
	ds_read_b128 v[126:129], v107 offset:2368
	s_waitcnt lgkmcnt(11)
	v_mfma_f32_16x16x32_bf16 v[12:15], v[58:61], v[16:19], 0
	s_waitcnt lgkmcnt(10)
	v_mfma_f32_16x16x32_bf16 v[12:15], v[74:77], v[20:23], v[12:15]
	s_waitcnt vmcnt(15) lgkmcnt(9)
	v_mfma_f32_16x16x32_bf16 v[12:15], v[150:153], v[54:57], v[12:15]
	v_lshl_add_u64 v[82:83], v[40:41], 0, s[98:99]
	v_lshl_add_u64 v[82:83], v[82:83], 0, v[30:31]
	global_load_dwordx4 v[150:153], v[82:83], off
	s_waitcnt vmcnt(15) lgkmcnt(8)
	v_mfma_f32_16x16x32_bf16 v[12:15], v[154:157], v[62:65], v[12:15]
	global_load_dwordx4 v[154:157], v[82:83], off offset:64
	s_waitcnt vmcnt(15) lgkmcnt(7)
	v_mfma_f32_16x16x32_bf16 v[12:15], v[158:161], v[66:69], v[12:15]
	global_load_dwordx4 v[158:161], v[82:83], off offset:128
	s_waitcnt vmcnt(15) lgkmcnt(6)
	v_mfma_f32_16x16x32_bf16 v[12:15], v[162:165], v[70:73], v[12:15]
	global_load_dwordx4 v[162:165], v[82:83], off offset:192
	s_waitcnt vmcnt(15) lgkmcnt(5)
	v_mfma_f32_16x16x32_bf16 v[12:15], v[166:169], v[24:27], v[12:15]
	v_lshl_add_u64 v[28:29], v[40:41], 0, s[100:101]
	v_lshl_add_u64 v[28:29], v[28:29], 0, v[30:31]
	global_load_dwordx4 v[166:169], v[28:29], off
	s_waitcnt vmcnt(15) lgkmcnt(4)
	v_mfma_f32_16x16x32_bf16 v[12:15], v[170:173], v[78:81], v[12:15]
	global_load_dwordx4 v[170:173], v[28:29], off offset:64
	s_waitcnt vmcnt(15) lgkmcnt(3)
	v_mfma_f32_16x16x32_bf16 v[12:15], v[186:189], v[114:117], v[12:15]
	global_load_dwordx4 v[186:189], v[28:29], off offset:128
	s_waitcnt vmcnt(15) lgkmcnt(2)
	v_mfma_f32_16x16x32_bf16 v[12:15], v[190:193], v[118:121], v[12:15]
	global_load_dwordx4 v[190:193], v[28:29], off offset:192
	ds_read_b128 v[58:61], v107 offset:4608
	ds_read_b128 v[74:77], v107 offset:4672
	s_waitcnt lgkmcnt(3)
	v_mfma_f32_16x16x32_bf16 v[8:11], v[122:125], v[16:19], 0
	s_waitcnt lgkmcnt(2)
	v_mfma_f32_16x16x32_bf16 v[8:11], v[126:129], v[20:23], v[8:11]
	s_waitcnt vmcnt(15)
	v_mfma_f32_16x16x32_bf16 v[8:11], v[194:197], v[54:57], v[8:11]
	v_lshl_add_u64 v[82:83], v[42:43], 0, s[98:99]
	v_lshl_add_u64 v[82:83], v[82:83], 0, v[30:31]
	global_load_dwordx4 v[194:197], v[82:83], off
	s_waitcnt vmcnt(15)
	v_mfma_f32_16x16x32_bf16 v[8:11], v[198:201], v[62:65], v[8:11]
	global_load_dwordx4 v[198:201], v[82:83], off offset:64
	v_mul_f32_e32 v130, v13, v13
	v_mul_f32_e32 v131, v15, v15
	v_fmac_f32_e32 v130, v12, v12
	v_fmac_f32_e32 v131, v14, v14
	v_add_f32_e32 v130, v130, v131
	v_mov_b32_e32 v132, v130
	s_waitcnt vmcnt(15)
	v_mfma_f32_16x16x32_bf16 v[8:11], v[202:205], v[66:69], v[8:11]
	global_load_dwordx4 v[202:205], v[82:83], off offset:128
	s_waitcnt vmcnt(15)
	v_mfma_f32_16x16x32_bf16 v[8:11], v[206:209], v[70:73], v[8:11]
	global_load_dwordx4 v[206:209], v[82:83], off offset:192
	s_waitcnt vmcnt(15)
	v_mfma_f32_16x16x32_bf16 v[8:11], v[228:231], v[24:27], v[8:11]
	v_lshl_add_u64 v[28:29], v[42:43], 0, s[100:101]
	v_lshl_add_u64 v[28:29], v[28:29], 0, v[30:31]
	global_load_dwordx4 v[228:231], v[28:29], off
	s_waitcnt vmcnt(15)
	v_mfma_f32_16x16x32_bf16 v[8:11], v[232:235], v[78:81], v[8:11]
	global_load_dwordx4 v[232:235], v[28:29], off offset:64
	s_waitcnt vmcnt(15)
	v_mfma_f32_16x16x32_bf16 v[8:11], v[236:239], v[114:117], v[8:11]
	global_load_dwordx4 v[236:239], v[28:29], off offset:128
	s_waitcnt vmcnt(15)
	v_mfma_f32_16x16x32_bf16 v[8:11], v[240:243], v[118:121], v[8:11]
	global_load_dwordx4 v[240:243], v[28:29], off offset:192
	ds_read_b128 v[122:125], v108
	ds_read_b128 v[126:129], v108 offset:64
	s_waitcnt lgkmcnt(3)
	v_mfma_f32_16x16x32_bf16 v[4:7], v[58:61], v[16:19], 0
	s_waitcnt lgkmcnt(2)
	v_mfma_f32_16x16x32_bf16 v[4:7], v[74:77], v[20:23], v[4:7]
	s_waitcnt vmcnt(15)
	v_mfma_f32_16x16x32_bf16 v[4:7], v[150:153], v[54:57], v[4:7]
	s_waitcnt vmcnt(14)
	v_mfma_f32_16x16x32_bf16 v[4:7], v[154:157], v[62:65], v[4:7]
	v_mul_f32_e32 v130, v9, v9
	v_mul_f32_e32 v131, v11, v11
	v_fmac_f32_e32 v130, v8, v8
	v_fmac_f32_e32 v131, v10, v10
	v_add_f32_e32 v130, v130, v131
	v_add_f32_e32 v132, v132, v130
	s_waitcnt vmcnt(13)
	v_mfma_f32_16x16x32_bf16 v[4:7], v[158:161], v[66:69], v[4:7]
	s_waitcnt vmcnt(12)
	v_mfma_f32_16x16x32_bf16 v[4:7], v[162:165], v[70:73], v[4:7]
	s_waitcnt vmcnt(11)
	v_mfma_f32_16x16x32_bf16 v[4:7], v[166:169], v[24:27], v[4:7]
	s_waitcnt vmcnt(10)
	v_mfma_f32_16x16x32_bf16 v[4:7], v[170:173], v[78:81], v[4:7]
	s_waitcnt vmcnt(9)
	v_mfma_f32_16x16x32_bf16 v[4:7], v[186:189], v[114:117], v[4:7]
	s_waitcnt vmcnt(8)
	v_mfma_f32_16x16x32_bf16 v[4:7], v[190:193], v[118:121], v[4:7]
	s_waitcnt lgkmcnt(1)
	v_mfma_f32_16x16x32_bf16 v[0:3], v[122:125], v[16:19], 0
	s_waitcnt lgkmcnt(0)
	v_mfma_f32_16x16x32_bf16 v[0:3], v[126:129], v[20:23], v[0:3]
	s_waitcnt vmcnt(7)
	v_mfma_f32_16x16x32_bf16 v[0:3], v[194:197], v[54:57], v[0:3]
	s_waitcnt vmcnt(6)
	v_mfma_f32_16x16x32_bf16 v[0:3], v[198:201], v[62:65], v[0:3]
	v_mul_f32_e32 v130, v5, v5
	v_mul_f32_e32 v131, v7, v7
	v_fmac_f32_e32 v130, v4, v4
	v_fmac_f32_e32 v131, v6, v6
	v_add_f32_e32 v130, v130, v131
	v_add_f32_e32 v132, v132, v130
	s_waitcnt vmcnt(5)
	v_mfma_f32_16x16x32_bf16 v[0:3], v[202:205], v[66:69], v[0:3]
	s_waitcnt vmcnt(4)
	v_mfma_f32_16x16x32_bf16 v[0:3], v[206:209], v[70:73], v[0:3]
	s_waitcnt vmcnt(3)
	v_mfma_f32_16x16x32_bf16 v[0:3], v[228:231], v[24:27], v[0:3]
	s_waitcnt vmcnt(2)
	v_mfma_f32_16x16x32_bf16 v[0:3], v[232:235], v[78:81], v[0:3]
	s_waitcnt vmcnt(1)
	v_mfma_f32_16x16x32_bf16 v[0:3], v[236:239], v[114:117], v[0:3]
	s_waitcnt vmcnt(0)
	v_mfma_f32_16x16x32_bf16 v[0:3], v[240:243], v[118:121], v[0:3]
	s_nop 7
	s_nop 1
	v_mul_f32_e32 v17, v1, v1
	v_mul_f32_e32 v18, v3, v3
	v_fmac_f32_e32 v17, v0, v0
	v_fmac_f32_e32 v18, v2, v2
	v_add_f32_e32 v17, v17, v18
	v_add_f32_e32 v16, v132, v17
	ds_bpermute_b32 v17, v101, v16
	s_waitcnt lgkmcnt(0)
	v_add_f32_e32 v16, v16, v17
	ds_bpermute_b32 v17, v102, v16
	s_and_saveexec_b64 s[0:1], s[42:43]
	s_cbranch_execz .LBB0_819
	s_waitcnt lgkmcnt(0)
	v_add_f32_e32 v16, v16, v17
	ds_write_b32 v99, v16 offset:27648
	s_branch .LBB0_819
